# deleted the 16 redundant back-to-back s_setprio 0 / s_setprio 1 pairs in the middle of the GEMM MFMA bursts
# baseline (speedup 1.0000x reference)
.LBB0_133:
	ds_read_b128 v[146:149], v155
	ds_read_b128 v[158:161], v155 offset:1024
	ds_read_b128 v[162:165], v155 offset:2048
	ds_read_b128 v[166:169], v155 offset:3072
	ds_read_b128 v[170:173], v156
	ds_read_b128 v[174:177], v156 offset:1024
	ds_read_b128 v[178:181], v156 offset:2048
	ds_read_b128 v[182:185], v156 offset:3072
	s_add_u32 s40, s34, 0xfffc0080
	s_addc_u32 s41, s35, -1
	s_cmp_eq_u32 s72, 12
	s_cselect_b32 s43, s3, s41
	s_cselect_b32 s42, s7, s40
	s_cselect_b32 s41, s17, s65
	s_cselect_b32 s40, s19, s64
	v_lshl_add_u64 v[150:151], s[34:35], 0, v[138:139]
	s_add_i32 m0, s50, 0xc000
	ds_read_b128 v[186:189], v157
	ds_read_b128 v[190:193], v157 offset:1024
	ds_read_b128 v[194:197], v157 offset:2048
	ds_read_b128 v[198:201], v157 offset:3072
	ds_read_b128 v[202:205], v157 offset:4096
	ds_read_b128 v[206:209], v157 offset:5120
	ds_read_b128 v[210:213], v157 offset:6144
	ds_read_b128 v[214:217], v157 offset:7168
	global_load_lds_dwordx4 v[150:151], off
	v_lshl_add_u64 v[150:151], s[34:35], 0, v[140:141]
	s_add_i32 m0, s50, 0xe000
	s_nop 0
	global_load_lds_dwordx4 v[150:151], off
	s_waitcnt vmcnt(8)
	s_waitcnt lgkmcnt(0)
	s_barrier
	s_setprio 1
	s_waitcnt lgkmcnt(0)
	v_mfma_f32_16x16x32_bf16 v[124:127], v[146:149], v[186:189], v[124:127]
	v_mfma_f32_16x16x32_bf16 v[120:123], v[162:165], v[186:189], v[120:123]
	v_mfma_f32_16x16x32_bf16 v[108:111], v[146:149], v[194:197], v[108:111]
	v_mfma_f32_16x16x32_bf16 v[104:107], v[162:165], v[194:197], v[104:107]
	v_mfma_f32_16x16x32_bf16 v[92:95], v[146:149], v[202:205], v[92:95]
	v_mfma_f32_16x16x32_bf16 v[88:91], v[162:165], v[202:205], v[88:91]
	v_mfma_f32_16x16x32_bf16 v[76:79], v[146:149], v[210:213], v[76:79]
	v_mfma_f32_16x16x32_bf16 v[72:75], v[162:165], v[210:213], v[72:75]
	v_mfma_f32_16x16x32_bf16 v[124:127], v[158:161], v[190:193], v[124:127]
	v_mfma_f32_16x16x32_bf16 v[120:123], v[166:169], v[190:193], v[120:123]
	v_mfma_f32_16x16x32_bf16 v[108:111], v[158:161], v[198:201], v[108:111]
	v_mfma_f32_16x16x32_bf16 v[104:107], v[166:169], v[198:201], v[104:107]
	v_mfma_f32_16x16x32_bf16 v[92:95], v[158:161], v[206:209], v[92:95]
	v_mfma_f32_16x16x32_bf16 v[88:91], v[166:169], v[206:209], v[88:91]
	v_mfma_f32_16x16x32_bf16 v[76:79], v[158:161], v[214:217], v[76:79]
	v_mfma_f32_16x16x32_bf16 v[72:75], v[166:169], v[214:217], v[72:75]
	v_mfma_f32_16x16x32_bf16 v[116:119], v[170:173], v[186:189], v[116:119]
	v_mfma_f32_16x16x32_bf16 v[112:115], v[178:181], v[186:189], v[112:115]
	v_mfma_f32_16x16x32_bf16 v[100:103], v[170:173], v[194:197], v[100:103]
	v_mfma_f32_16x16x32_bf16 v[96:99], v[178:181], v[194:197], v[96:99]
	v_mfma_f32_16x16x32_bf16 v[84:87], v[170:173], v[202:205], v[84:87]
	v_mfma_f32_16x16x32_bf16 v[80:83], v[178:181], v[202:205], v[80:83]
	v_mfma_f32_16x16x32_bf16 v[68:71], v[170:173], v[210:213], v[68:71]
	v_mfma_f32_16x16x32_bf16 v[64:67], v[178:181], v[210:213], v[64:67]
	v_mfma_f32_16x16x32_bf16 v[116:119], v[174:177], v[190:193], v[116:119]
	v_mfma_f32_16x16x32_bf16 v[112:115], v[182:185], v[190:193], v[112:115]
	v_mfma_f32_16x16x32_bf16 v[100:103], v[174:177], v[198:201], v[100:103]
	v_mfma_f32_16x16x32_bf16 v[96:99], v[182:185], v[198:201], v[96:99]
	v_mfma_f32_16x16x32_bf16 v[84:87], v[174:177], v[206:209], v[84:87]
	v_mfma_f32_16x16x32_bf16 v[80:83], v[182:185], v[206:209], v[80:83]
	v_mfma_f32_16x16x32_bf16 v[68:71], v[174:177], v[214:217], v[68:71]
	v_mfma_f32_16x16x32_bf16 v[64:67], v[182:185], v[214:217], v[64:67]
	s_setprio 0
	s_barrier
	s_add_i32 s73, s59, s45
	v_lshl_add_u64 v[150:151], s[40:41], 0, v[130:131]
	s_mov_b32 m0, s73
	ds_read_b128 v[186:189], v157 offset:16384
	ds_read_b128 v[190:193], v157 offset:17408
	ds_read_b128 v[194:197], v157 offset:18432
	ds_read_b128 v[198:201], v157 offset:19456
	ds_read_b128 v[202:205], v157 offset:20480
	ds_read_b128 v[206:209], v157 offset:21504
	ds_read_b128 v[210:213], v157 offset:22528
	ds_read_b128 v[214:217], v157 offset:23552
	global_load_lds_dwordx4 v[150:151], off
	s_add_i32 m0, s73, 0x2000
	s_add_u32 s74, s40, 0x40000
	v_lshl_add_u64 v[218:219], s[40:41], 0, v[134:135]
	s_addc_u32 s75, s41, 0
	s_add_i32 s73, s60, s45
	global_load_lds_dwordx4 v[218:219], off
	v_lshl_add_u64 v[220:221], s[74:75], 0, v[130:131]
	s_mov_b32 m0, s73
	v_lshl_add_u64 v[224:225], s[42:43], 0, v[132:133]
	global_load_lds_dwordx4 v[220:221], off
	v_lshl_add_u64 v[220:221], s[74:75], 0, v[134:135]
	s_add_i32 m0, s73, 0x2000
	s_nop 0
	global_load_lds_dwordx4 v[220:221], off
	v_lshl_add_u64 v[220:221], s[42:43], 0, v[128:129]
	s_mov_b32 m0, s50
	s_nop 0
	global_load_lds_dwordx4 v[220:221], off
	s_mov_b32 m0, s51
	s_nop 0
	global_load_lds_dwordx4 v[224:225], off
	s_waitcnt vmcnt(8)
	s_waitcnt lgkmcnt(0)
	s_barrier
	s_setprio 1
	s_waitcnt lgkmcnt(0)
	v_mfma_f32_16x16x32_bf16 v[60:63], v[146:149], v[186:189], v[60:63]
	v_mfma_f32_16x16x32_bf16 v[56:59], v[162:165], v[186:189], v[56:59]
	v_mfma_f32_16x16x32_bf16 v[44:47], v[146:149], v[194:197], v[44:47]
	v_mfma_f32_16x16x32_bf16 v[40:43], v[162:165], v[194:197], v[40:43]
	v_mfma_f32_16x16x32_bf16 v[28:31], v[146:149], v[202:205], v[28:31]
	v_mfma_f32_16x16x32_bf16 v[24:27], v[162:165], v[202:205], v[24:27]
	v_mfma_f32_16x16x32_bf16 v[12:15], v[146:149], v[210:213], v[12:15]
	v_mfma_f32_16x16x32_bf16 v[8:11], v[162:165], v[210:213], v[8:11]
	v_mfma_f32_16x16x32_bf16 v[60:63], v[158:161], v[190:193], v[60:63]
	v_mfma_f32_16x16x32_bf16 v[56:59], v[166:169], v[190:193], v[56:59]
	v_mfma_f32_16x16x32_bf16 v[44:47], v[158:161], v[198:201], v[44:47]
	v_mfma_f32_16x16x32_bf16 v[40:43], v[166:169], v[198:201], v[40:43]
	v_mfma_f32_16x16x32_bf16 v[28:31], v[158:161], v[206:209], v[28:31]
	v_mfma_f32_16x16x32_bf16 v[24:27], v[166:169], v[206:209], v[24:27]
	v_mfma_f32_16x16x32_bf16 v[12:15], v[158:161], v[214:217], v[12:15]
	v_mfma_f32_16x16x32_bf16 v[8:11], v[166:169], v[214:217], v[8:11]
	v_mfma_f32_16x16x32_bf16 v[52:55], v[170:173], v[186:189], v[52:55]
	v_mfma_f32_16x16x32_bf16 v[48:51], v[178:181], v[186:189], v[48:51]
	v_mfma_f32_16x16x32_bf16 v[36:39], v[170:173], v[194:197], v[36:39]
	v_mfma_f32_16x16x32_bf16 v[32:35], v[178:181], v[194:197], v[32:35]
	v_mfma_f32_16x16x32_bf16 v[20:23], v[170:173], v[202:205], v[20:23]
	v_mfma_f32_16x16x32_bf16 v[16:19], v[178:181], v[202:205], v[16:19]
	v_mfma_f32_16x16x32_bf16 v[4:7], v[170:173], v[210:213], v[4:7]
	v_mfma_f32_16x16x32_bf16 v[0:3], v[178:181], v[210:213], v[0:3]
	v_mfma_f32_16x16x32_bf16 v[52:55], v[174:177], v[190:193], v[52:55]
	v_mfma_f32_16x16x32_bf16 v[48:51], v[182:185], v[190:193], v[48:51]
	v_mfma_f32_16x16x32_bf16 v[36:39], v[174:177], v[198:201], v[36:39]
	v_mfma_f32_16x16x32_bf16 v[32:35], v[182:185], v[198:201], v[32:35]
	v_mfma_f32_16x16x32_bf16 v[20:23], v[174:177], v[206:209], v[20:23]
	v_mfma_f32_16x16x32_bf16 v[16:19], v[182:185], v[206:209], v[16:19]
	v_mfma_f32_16x16x32_bf16 v[4:7], v[174:177], v[214:217], v[4:7]
	v_mfma_f32_16x16x32_bf16 v[0:3], v[182:185], v[214:217], v[0:3]
	s_setprio 0
	s_barrier
	s_add_i32 s73, 0, 0x18000
	v_add_u32_e32 v136, s73, v154
	s_add_i32 s74, 0, 0x1c000
	ds_read_b128 v[146:149], v136
	ds_read_b128 v[158:161], v136 offset:1024
	ds_read_b128 v[162:165], v136 offset:2048
	ds_read_b128 v[166:169], v136 offset:3072
	v_add_u32_e32 v136, s74, v154
	ds_read_b128 v[170:173], v136
	ds_read_b128 v[174:177], v136 offset:1024
	ds_read_b128 v[178:181], v136 offset:2048
	ds_read_b128 v[182:185], v136 offset:3072
	s_add_u32 s42, s42, 0x40000
	s_addc_u32 s43, s43, 0
	s_mov_b32 m0, s52
	v_lshl_add_u64 v[226:227], s[42:43], 0, v[128:129]
	ds_read_b128 v[186:189], v157 offset:32768
	ds_read_b128 v[190:193], v157 offset:33792
	ds_read_b128 v[194:197], v157 offset:34816
	ds_read_b128 v[198:201], v157 offset:35840
	ds_read_b128 v[202:205], v157 offset:36864
	ds_read_b128 v[206:209], v157 offset:37888
	ds_read_b128 v[210:213], v157 offset:38912
	ds_read_b128 v[214:217], v157 offset:39936
	global_load_lds_dwordx4 v[226:227], off
	v_lshl_add_u64 v[226:227], s[42:43], 0, v[132:133]
	s_mov_b32 m0, s53
	s_nop 0
	global_load_lds_dwordx4 v[226:227], off
	s_waitcnt vmcnt(8)
	s_waitcnt lgkmcnt(0)
	s_barrier
	s_setprio 1
	s_waitcnt lgkmcnt(0)
	v_mfma_f32_16x16x32_bf16 v[124:127], v[146:149], v[186:189], v[124:127]
	v_mfma_f32_16x16x32_bf16 v[120:123], v[162:165], v[186:189], v[120:123]
	v_mfma_f32_16x16x32_bf16 v[108:111], v[146:149], v[194:197], v[108:111]
	v_mfma_f32_16x16x32_bf16 v[104:107], v[162:165], v[194:197], v[104:107]
	v_mfma_f32_16x16x32_bf16 v[92:95], v[146:149], v[202:205], v[92:95]
	v_mfma_f32_16x16x32_bf16 v[88:91], v[162:165], v[202:205], v[88:91]
	v_mfma_f32_16x16x32_bf16 v[76:79], v[146:149], v[210:213], v[76:79]
	v_mfma_f32_16x16x32_bf16 v[72:75], v[162:165], v[210:213], v[72:75]
	v_mfma_f32_16x16x32_bf16 v[124:127], v[158:161], v[190:193], v[124:127]
	v_mfma_f32_16x16x32_bf16 v[120:123], v[166:169], v[190:193], v[120:123]
	v_mfma_f32_16x16x32_bf16 v[108:111], v[158:161], v[198:201], v[108:111]
	v_mfma_f32_16x16x32_bf16 v[104:107], v[166:169], v[198:201], v[104:107]
	v_mfma_f32_16x16x32_bf16 v[92:95], v[158:161], v[206:209], v[92:95]
	v_mfma_f32_16x16x32_bf16 v[88:91], v[166:169], v[206:209], v[88:91]
	v_mfma_f32_16x16x32_bf16 v[76:79], v[158:161], v[214:217], v[76:79]
	v_mfma_f32_16x16x32_bf16 v[72:75], v[166:169], v[214:217], v[72:75]
	v_mfma_f32_16x16x32_bf16 v[116:119], v[170:173], v[186:189], v[116:119]
	v_mfma_f32_16x16x32_bf16 v[112:115], v[178:181], v[186:189], v[112:115]
	v_mfma_f32_16x16x32_bf16 v[100:103], v[170:173], v[194:197], v[100:103]
	v_mfma_f32_16x16x32_bf16 v[96:99], v[178:181], v[194:197], v[96:99]
	v_mfma_f32_16x16x32_bf16 v[84:87], v[170:173], v[202:205], v[84:87]
	v_mfma_f32_16x16x32_bf16 v[80:83], v[178:181], v[202:205], v[80:83]
	v_mfma_f32_16x16x32_bf16 v[68:71], v[170:173], v[210:213], v[68:71]
	v_mfma_f32_16x16x32_bf16 v[64:67], v[178:181], v[210:213], v[64:67]
	v_mfma_f32_16x16x32_bf16 v[116:119], v[174:177], v[190:193], v[116:119]
	v_mfma_f32_16x16x32_bf16 v[112:115], v[182:185], v[190:193], v[112:115]
	v_mfma_f32_16x16x32_bf16 v[100:103], v[174:177], v[198:201], v[100:103]
	v_mfma_f32_16x16x32_bf16 v[96:99], v[182:185], v[198:201], v[96:99]
	v_mfma_f32_16x16x32_bf16 v[84:87], v[174:177], v[206:209], v[84:87]
	v_mfma_f32_16x16x32_bf16 v[80:83], v[182:185], v[206:209], v[80:83]
	v_mfma_f32_16x16x32_bf16 v[68:71], v[174:177], v[214:217], v[68:71]
	v_mfma_f32_16x16x32_bf16 v[64:67], v[182:185], v[214:217], v[64:67]
	s_setprio 0
	s_barrier
	s_add_i32 s42, s73, s45
	v_lshl_add_u64 v[150:151], v[150:151], 0, s[10:11]
	s_mov_b32 m0, s42
	ds_read_b128 v[186:189], v157 offset:49152
	ds_read_b128 v[190:193], v157 offset:50176
	ds_read_b128 v[194:197], v157 offset:51200
	ds_read_b128 v[198:201], v157 offset:52224
	ds_read_b128 v[202:205], v157 offset:53248
	ds_read_b128 v[206:209], v157 offset:54272
	ds_read_b128 v[210:213], v157 offset:55296
	ds_read_b128 v[214:217], v157 offset:56320
	global_load_lds_dwordx4 v[150:151], off
	s_add_i32 m0, s42, 0x2000
	s_add_u32 s40, s40, 0x40080
	v_lshl_add_u64 v[150:151], v[218:219], 0, s[10:11]
	s_addc_u32 s41, s41, 0
	s_add_i32 s42, s74, s45
	global_load_lds_dwordx4 v[150:151], off
	v_lshl_add_u64 v[150:151], s[40:41], 0, v[130:131]
	s_mov_b32 m0, s42
	s_nop 0
	global_load_lds_dwordx4 v[150:151], off
	v_lshl_add_u64 v[150:151], s[40:41], 0, v[134:135]
	s_add_i32 m0, s42, 0x2000
	s_nop 0
	global_load_lds_dwordx4 v[150:151], off
	v_lshl_add_u64 v[150:151], v[220:221], 0, s[10:11]
	s_mov_b32 m0, s57
	s_nop 0
	global_load_lds_dwordx4 v[150:151], off
	v_lshl_add_u64 v[150:151], v[224:225], 0, s[10:11]
	s_mov_b32 m0, s58
	s_nop 0
	global_load_lds_dwordx4 v[150:151], off
	s_waitcnt vmcnt(8)
	s_waitcnt lgkmcnt(0)
	s_barrier
	s_setprio 1
	s_waitcnt lgkmcnt(0)
	v_mfma_f32_16x16x32_bf16 v[60:63], v[146:149], v[186:189], v[60:63]
	v_mfma_f32_16x16x32_bf16 v[56:59], v[162:165], v[186:189], v[56:59]
	v_mfma_f32_16x16x32_bf16 v[44:47], v[146:149], v[194:197], v[44:47]
	v_mfma_f32_16x16x32_bf16 v[40:43], v[162:165], v[194:197], v[40:43]
	v_mfma_f32_16x16x32_bf16 v[28:31], v[146:149], v[202:205], v[28:31]
	v_mfma_f32_16x16x32_bf16 v[24:27], v[162:165], v[202:205], v[24:27]
	v_mfma_f32_16x16x32_bf16 v[12:15], v[146:149], v[210:213], v[12:15]
	v_mfma_f32_16x16x32_bf16 v[8:11], v[162:165], v[210:213], v[8:11]
	v_mfma_f32_16x16x32_bf16 v[60:63], v[158:161], v[190:193], v[60:63]
	v_mfma_f32_16x16x32_bf16 v[56:59], v[166:169], v[190:193], v[56:59]
	v_mfma_f32_16x16x32_bf16 v[44:47], v[158:161], v[198:201], v[44:47]
	v_mfma_f32_16x16x32_bf16 v[40:43], v[166:169], v[198:201], v[40:43]
	v_mfma_f32_16x16x32_bf16 v[28:31], v[158:161], v[206:209], v[28:31]
	v_mfma_f32_16x16x32_bf16 v[24:27], v[166:169], v[206:209], v[24:27]
	v_mfma_f32_16x16x32_bf16 v[12:15], v[158:161], v[214:217], v[12:15]
	v_mfma_f32_16x16x32_bf16 v[8:11], v[166:169], v[214:217], v[8:11]
	v_mfma_f32_16x16x32_bf16 v[52:55], v[170:173], v[186:189], v[52:55]
	v_mfma_f32_16x16x32_bf16 v[48:51], v[178:181], v[186:189], v[48:51]
	v_mfma_f32_16x16x32_bf16 v[36:39], v[170:173], v[194:197], v[36:39]
	v_mfma_f32_16x16x32_bf16 v[32:35], v[178:181], v[194:197], v[32:35]
	v_mfma_f32_16x16x32_bf16 v[20:23], v[170:173], v[202:205], v[20:23]
	v_mfma_f32_16x16x32_bf16 v[16:19], v[178:181], v[202:205], v[16:19]
	v_mfma_f32_16x16x32_bf16 v[4:7], v[170:173], v[210:213], v[4:7]
	v_mfma_f32_16x16x32_bf16 v[0:3], v[178:181], v[210:213], v[0:3]
	v_mfma_f32_16x16x32_bf16 v[52:55], v[174:177], v[190:193], v[52:55]
	v_mfma_f32_16x16x32_bf16 v[48:51], v[182:185], v[190:193], v[48:51]
	v_mfma_f32_16x16x32_bf16 v[36:39], v[174:177], v[198:201], v[36:39]
	v_mfma_f32_16x16x32_bf16 v[32:35], v[182:185], v[198:201], v[32:35]
	v_mfma_f32_16x16x32_bf16 v[20:23], v[174:177], v[206:209], v[20:23]
	v_mfma_f32_16x16x32_bf16 v[16:19], v[182:185], v[206:209], v[16:19]
	v_mfma_f32_16x16x32_bf16 v[4:7], v[174:177], v[214:217], v[4:7]
	v_mfma_f32_16x16x32_bf16 v[0:3], v[182:185], v[214:217], v[0:3]
	s_setprio 0
	s_barrier
	s_add_i32 s72, s72, 2
	s_add_u32 s34, s34, 0x100
	s_addc_u32 s35, s35, 0
	s_add_u32 s64, s64, 0x100
	s_addc_u32 s65, s65, 0
	s_cmp_gt_u32 s72, 13
	s_cbranch_scc0 .LBB0_133
	s_and_b64 vcc, exec, s[12:13]
	s_cbranch_vccz .LBB0_136
	s_barrier

.LBB0_606:
	ds_read_b128 v[128:131], v227
	ds_read_b128 v[132:135], v227 offset:1024
	ds_read_b128 v[136:139], v227 offset:2048
	ds_read_b128 v[140:143], v227 offset:3072
	ds_read_b128 v[144:147], v228
	ds_read_b128 v[148:151], v228 offset:1024
	ds_read_b128 v[152:155], v228 offset:2048
	ds_read_b128 v[156:159], v228 offset:3072
	s_add_u32 s10, s8, 0xfffc0080
	s_addc_u32 s11, s9, -1
	s_cmp_eq_u32 s61, 12
	s_cselect_b32 s13, s1, s11
	s_cselect_b32 s12, s37, s10
	s_cselect_b32 s11, s31, s60
	s_cselect_b32 s10, s58, s59
	v_lshl_add_u64 v[208:209], s[8:9], 0, v[200:201]
	s_add_i32 m0, s3, 0xc000
	ds_read_b128 v[160:163], v229
	ds_read_b128 v[164:167], v229 offset:1024
	ds_read_b128 v[168:171], v229 offset:2048
	ds_read_b128 v[172:175], v229 offset:3072
	ds_read_b128 v[176:179], v229 offset:4096
	ds_read_b128 v[180:183], v229 offset:5120
	ds_read_b128 v[184:187], v229 offset:6144
	ds_read_b128 v[188:191], v229 offset:7168
	global_load_lds_dwordx4 v[208:209], off
	v_lshl_add_u64 v[208:209], s[8:9], 0, v[202:203]
	s_add_i32 m0, s3, 0xe000
	s_nop 0
	global_load_lds_dwordx4 v[208:209], off
	s_waitcnt vmcnt(8)
	s_waitcnt lgkmcnt(0)
	s_barrier
	s_setprio 1
	s_waitcnt lgkmcnt(0)
	v_mfma_f32_16x16x32_bf16 v[124:127], v[128:131], v[160:163], v[124:127]
	v_mfma_f32_16x16x32_bf16 v[120:123], v[136:139], v[160:163], v[120:123]
	v_mfma_f32_16x16x32_bf16 v[108:111], v[128:131], v[168:171], v[108:111]
	v_mfma_f32_16x16x32_bf16 v[104:107], v[136:139], v[168:171], v[104:107]
	v_mfma_f32_16x16x32_bf16 v[92:95], v[128:131], v[176:179], v[92:95]
	v_mfma_f32_16x16x32_bf16 v[88:91], v[136:139], v[176:179], v[88:91]
	v_mfma_f32_16x16x32_bf16 v[76:79], v[128:131], v[184:187], v[76:79]
	v_mfma_f32_16x16x32_bf16 v[72:75], v[136:139], v[184:187], v[72:75]
	v_mfma_f32_16x16x32_bf16 v[124:127], v[132:135], v[164:167], v[124:127]
	v_mfma_f32_16x16x32_bf16 v[120:123], v[140:143], v[164:167], v[120:123]
	v_mfma_f32_16x16x32_bf16 v[108:111], v[132:135], v[172:175], v[108:111]
	v_mfma_f32_16x16x32_bf16 v[104:107], v[140:143], v[172:175], v[104:107]
	v_mfma_f32_16x16x32_bf16 v[92:95], v[132:135], v[180:183], v[92:95]
	v_mfma_f32_16x16x32_bf16 v[88:91], v[140:143], v[180:183], v[88:91]
	v_mfma_f32_16x16x32_bf16 v[76:79], v[132:135], v[188:191], v[76:79]
	v_mfma_f32_16x16x32_bf16 v[72:75], v[140:143], v[188:191], v[72:75]
	v_mfma_f32_16x16x32_bf16 v[116:119], v[144:147], v[160:163], v[116:119]
	v_mfma_f32_16x16x32_bf16 v[112:115], v[152:155], v[160:163], v[112:115]
	v_mfma_f32_16x16x32_bf16 v[100:103], v[144:147], v[168:171], v[100:103]
	v_mfma_f32_16x16x32_bf16 v[96:99], v[152:155], v[168:171], v[96:99]
	v_mfma_f32_16x16x32_bf16 v[84:87], v[144:147], v[176:179], v[84:87]
	v_mfma_f32_16x16x32_bf16 v[80:83], v[152:155], v[176:179], v[80:83]
	v_mfma_f32_16x16x32_bf16 v[68:71], v[144:147], v[184:187], v[68:71]
	v_mfma_f32_16x16x32_bf16 v[64:67], v[152:155], v[184:187], v[64:67]
	v_mfma_f32_16x16x32_bf16 v[116:119], v[148:151], v[164:167], v[116:119]
	v_mfma_f32_16x16x32_bf16 v[112:115], v[156:159], v[164:167], v[112:115]
	v_mfma_f32_16x16x32_bf16 v[100:103], v[148:151], v[172:175], v[100:103]
	v_mfma_f32_16x16x32_bf16 v[96:99], v[156:159], v[172:175], v[96:99]
	v_mfma_f32_16x16x32_bf16 v[84:87], v[148:151], v[180:183], v[84:87]
	v_mfma_f32_16x16x32_bf16 v[80:83], v[156:159], v[180:183], v[80:83]
	v_mfma_f32_16x16x32_bf16 v[68:71], v[148:151], v[188:191], v[68:71]
	v_mfma_f32_16x16x32_bf16 v[64:67], v[156:159], v[188:191], v[64:67]
	s_setprio 0
	s_barrier
	s_add_i32 s62, s55, s33
	v_lshl_add_u64 v[208:209], s[10:11], 0, v[194:195]
	s_mov_b32 m0, s62
	ds_read_b128 v[160:163], v229 offset:16384
	ds_read_b128 v[164:167], v229 offset:17408
	ds_read_b128 v[168:171], v229 offset:18432
	ds_read_b128 v[172:175], v229 offset:19456
	ds_read_b128 v[176:179], v229 offset:20480
	ds_read_b128 v[180:183], v229 offset:21504
	ds_read_b128 v[184:187], v229 offset:22528
	ds_read_b128 v[188:191], v229 offset:23552
	global_load_lds_dwordx4 v[208:209], off
	s_add_i32 m0, s62, 0x2000
	s_add_u32 s62, s10, 0x40000
	v_lshl_add_u64 v[210:211], s[10:11], 0, v[198:199]
	s_addc_u32 s63, s11, 0
	s_add_i32 s64, s56, s33
	global_load_lds_dwordx4 v[210:211], off
	v_lshl_add_u64 v[212:213], s[62:63], 0, v[194:195]
	s_mov_b32 m0, s64
	v_lshl_add_u64 v[214:215], s[12:13], 0, v[196:197]
	global_load_lds_dwordx4 v[212:213], off
	v_lshl_add_u64 v[212:213], s[62:63], 0, v[198:199]
	s_add_i32 m0, s64, 0x2000
	s_nop 0
	global_load_lds_dwordx4 v[212:213], off
	v_lshl_add_u64 v[212:213], s[12:13], 0, v[192:193]
	s_mov_b32 m0, s3
	s_nop 0
	global_load_lds_dwordx4 v[212:213], off
	s_mov_b32 m0, s42
	s_nop 0
	global_load_lds_dwordx4 v[214:215], off
	s_waitcnt vmcnt(8)
	s_waitcnt lgkmcnt(0)
	s_barrier
	s_setprio 1
	s_waitcnt lgkmcnt(0)
	v_mfma_f32_16x16x32_bf16 v[60:63], v[128:131], v[160:163], v[60:63]
	v_mfma_f32_16x16x32_bf16 v[56:59], v[136:139], v[160:163], v[56:59]
	v_mfma_f32_16x16x32_bf16 v[44:47], v[128:131], v[168:171], v[44:47]
	v_mfma_f32_16x16x32_bf16 v[40:43], v[136:139], v[168:171], v[40:43]
	v_mfma_f32_16x16x32_bf16 v[28:31], v[128:131], v[176:179], v[28:31]
	v_mfma_f32_16x16x32_bf16 v[24:27], v[136:139], v[176:179], v[24:27]
	v_mfma_f32_16x16x32_bf16 v[12:15], v[128:131], v[184:187], v[12:15]
	v_mfma_f32_16x16x32_bf16 v[8:11], v[136:139], v[184:187], v[8:11]
	v_mfma_f32_16x16x32_bf16 v[60:63], v[132:135], v[164:167], v[60:63]
	v_mfma_f32_16x16x32_bf16 v[56:59], v[140:143], v[164:167], v[56:59]
	v_mfma_f32_16x16x32_bf16 v[44:47], v[132:135], v[172:175], v[44:47]
	v_mfma_f32_16x16x32_bf16 v[40:43], v[140:143], v[172:175], v[40:43]
	v_mfma_f32_16x16x32_bf16 v[28:31], v[132:135], v[180:183], v[28:31]
	v_mfma_f32_16x16x32_bf16 v[24:27], v[140:143], v[180:183], v[24:27]
	v_mfma_f32_16x16x32_bf16 v[12:15], v[132:135], v[188:191], v[12:15]
	v_mfma_f32_16x16x32_bf16 v[8:11], v[140:143], v[188:191], v[8:11]
	v_mfma_f32_16x16x32_bf16 v[52:55], v[144:147], v[160:163], v[52:55]
	v_mfma_f32_16x16x32_bf16 v[48:51], v[152:155], v[160:163], v[48:51]
	v_mfma_f32_16x16x32_bf16 v[36:39], v[144:147], v[168:171], v[36:39]
	v_mfma_f32_16x16x32_bf16 v[32:35], v[152:155], v[168:171], v[32:35]
	v_mfma_f32_16x16x32_bf16 v[20:23], v[144:147], v[176:179], v[20:23]
	v_mfma_f32_16x16x32_bf16 v[16:19], v[152:155], v[176:179], v[16:19]
	v_mfma_f32_16x16x32_bf16 v[4:7], v[144:147], v[184:187], v[4:7]
	v_mfma_f32_16x16x32_bf16 v[0:3], v[152:155], v[184:187], v[0:3]
	v_mfma_f32_16x16x32_bf16 v[52:55], v[148:151], v[164:167], v[52:55]
	v_mfma_f32_16x16x32_bf16 v[48:51], v[156:159], v[164:167], v[48:51]
	v_mfma_f32_16x16x32_bf16 v[36:39], v[148:151], v[172:175], v[36:39]
	v_mfma_f32_16x16x32_bf16 v[32:35], v[156:159], v[172:175], v[32:35]
	v_mfma_f32_16x16x32_bf16 v[20:23], v[148:151], v[180:183], v[20:23]
	v_mfma_f32_16x16x32_bf16 v[16:19], v[156:159], v[180:183], v[16:19]
	v_mfma_f32_16x16x32_bf16 v[4:7], v[148:151], v[188:191], v[4:7]
	v_mfma_f32_16x16x32_bf16 v[0:3], v[156:159], v[188:191], v[0:3]
	s_setprio 0
	s_barrier
	s_add_i32 s62, 0, 0x18000
	s_add_i32 s63, 0, 0x1c000
	v_add_u32_e32 v140, s62, v226
	v_add_u32_e32 v156, s63, v226
	ds_read_b128 v[128:131], v140
	ds_read_b128 v[132:135], v140 offset:1024
	ds_read_b128 v[136:139], v140 offset:2048
	ds_read_b128 v[140:143], v140 offset:3072
	ds_read_b128 v[144:147], v156
	ds_read_b128 v[148:151], v156 offset:1024
	ds_read_b128 v[152:155], v156 offset:2048
	ds_read_b128 v[156:159], v156 offset:3072
	s_add_u32 s12, s12, 0x40000
	s_addc_u32 s13, s13, 0
	s_mov_b32 m0, s43
	v_lshl_add_u64 v[216:217], s[12:13], 0, v[192:193]
	ds_read_b128 v[160:163], v229 offset:32768
	ds_read_b128 v[164:167], v229 offset:33792
	ds_read_b128 v[168:171], v229 offset:34816
	ds_read_b128 v[172:175], v229 offset:35840
	ds_read_b128 v[176:179], v229 offset:36864
	ds_read_b128 v[180:183], v229 offset:37888
	ds_read_b128 v[184:187], v229 offset:38912
	ds_read_b128 v[188:191], v229 offset:39936
	global_load_lds_dwordx4 v[216:217], off
	v_lshl_add_u64 v[216:217], s[12:13], 0, v[196:197]
	s_mov_b32 m0, s44
	s_nop 0
	global_load_lds_dwordx4 v[216:217], off
	s_waitcnt vmcnt(8)
	s_waitcnt lgkmcnt(0)
	s_barrier
	s_setprio 1
	s_waitcnt lgkmcnt(0)
	v_mfma_f32_16x16x32_bf16 v[124:127], v[128:131], v[160:163], v[124:127]
	v_mfma_f32_16x16x32_bf16 v[120:123], v[136:139], v[160:163], v[120:123]
	v_mfma_f32_16x16x32_bf16 v[108:111], v[128:131], v[168:171], v[108:111]
	v_mfma_f32_16x16x32_bf16 v[104:107], v[136:139], v[168:171], v[104:107]
	v_mfma_f32_16x16x32_bf16 v[92:95], v[128:131], v[176:179], v[92:95]
	v_mfma_f32_16x16x32_bf16 v[88:91], v[136:139], v[176:179], v[88:91]
	v_mfma_f32_16x16x32_bf16 v[76:79], v[128:131], v[184:187], v[76:79]
	v_mfma_f32_16x16x32_bf16 v[72:75], v[136:139], v[184:187], v[72:75]
	v_mfma_f32_16x16x32_bf16 v[124:127], v[132:135], v[164:167], v[124:127]
	v_mfma_f32_16x16x32_bf16 v[120:123], v[140:143], v[164:167], v[120:123]
	v_mfma_f32_16x16x32_bf16 v[108:111], v[132:135], v[172:175], v[108:111]
	v_mfma_f32_16x16x32_bf16 v[104:107], v[140:143], v[172:175], v[104:107]
	v_mfma_f32_16x16x32_bf16 v[92:95], v[132:135], v[180:183], v[92:95]
	v_mfma_f32_16x16x32_bf16 v[88:91], v[140:143], v[180:183], v[88:91]
	v_mfma_f32_16x16x32_bf16 v[76:79], v[132:135], v[188:191], v[76:79]
	v_mfma_f32_16x16x32_bf16 v[72:75], v[140:143], v[188:191], v[72:75]
	v_mfma_f32_16x16x32_bf16 v[116:119], v[144:147], v[160:163], v[116:119]
	v_mfma_f32_16x16x32_bf16 v[112:115], v[152:155], v[160:163], v[112:115]
	v_mfma_f32_16x16x32_bf16 v[100:103], v[144:147], v[168:171], v[100:103]
	v_mfma_f32_16x16x32_bf16 v[96:99], v[152:155], v[168:171], v[96:99]
	v_mfma_f32_16x16x32_bf16 v[84:87], v[144:147], v[176:179], v[84:87]
	v_mfma_f32_16x16x32_bf16 v[80:83], v[152:155], v[176:179], v[80:83]
	v_mfma_f32_16x16x32_bf16 v[68:71], v[144:147], v[184:187], v[68:71]
	v_mfma_f32_16x16x32_bf16 v[64:67], v[152:155], v[184:187], v[64:67]
	v_mfma_f32_16x16x32_bf16 v[116:119], v[148:151], v[164:167], v[116:119]
	v_mfma_f32_16x16x32_bf16 v[112:115], v[156:159], v[164:167], v[112:115]
	v_mfma_f32_16x16x32_bf16 v[100:103], v[148:151], v[172:175], v[100:103]
	v_mfma_f32_16x16x32_bf16 v[96:99], v[156:159], v[172:175], v[96:99]
	v_mfma_f32_16x16x32_bf16 v[84:87], v[148:151], v[180:183], v[84:87]
	v_mfma_f32_16x16x32_bf16 v[80:83], v[156:159], v[180:183], v[80:83]
	v_mfma_f32_16x16x32_bf16 v[68:71], v[148:151], v[188:191], v[68:71]
	v_mfma_f32_16x16x32_bf16 v[64:67], v[156:159], v[188:191], v[64:67]
	s_setprio 0
	s_barrier
	s_add_i32 s12, s62, s33
	v_lshl_add_u64 v[208:209], v[208:209], 0, s[16:17]
	s_mov_b32 m0, s12
	ds_read_b128 v[160:163], v229 offset:49152
	ds_read_b128 v[164:167], v229 offset:50176
	ds_read_b128 v[168:171], v229 offset:51200
	ds_read_b128 v[172:175], v229 offset:52224
	ds_read_b128 v[176:179], v229 offset:53248
	ds_read_b128 v[180:183], v229 offset:54272
	ds_read_b128 v[184:187], v229 offset:55296
	ds_read_b128 v[188:191], v229 offset:56320
	global_load_lds_dwordx4 v[208:209], off
	s_add_i32 m0, s12, 0x2000
	s_add_u32 s10, s10, 0x40080
	v_lshl_add_u64 v[208:209], v[210:211], 0, s[16:17]
	s_addc_u32 s11, s11, 0
	s_add_i32 s12, s63, s33
	global_load_lds_dwordx4 v[208:209], off
	v_lshl_add_u64 v[208:209], s[10:11], 0, v[194:195]
	s_mov_b32 m0, s12
	s_nop 0
	global_load_lds_dwordx4 v[208:209], off
	v_lshl_add_u64 v[208:209], s[10:11], 0, v[198:199]
	s_add_i32 m0, s12, 0x2000
	s_nop 0
	global_load_lds_dwordx4 v[208:209], off
	v_lshl_add_u64 v[208:209], v[212:213], 0, s[16:17]
	s_mov_b32 m0, s53
	s_nop 0
	global_load_lds_dwordx4 v[208:209], off
	v_lshl_add_u64 v[208:209], v[214:215], 0, s[16:17]
	s_mov_b32 m0, s54
	s_nop 0
	global_load_lds_dwordx4 v[208:209], off
	s_waitcnt vmcnt(8)
	s_waitcnt lgkmcnt(0)
	s_barrier
	s_setprio 1
	s_waitcnt lgkmcnt(0)
	v_mfma_f32_16x16x32_bf16 v[60:63], v[128:131], v[160:163], v[60:63]
	v_mfma_f32_16x16x32_bf16 v[56:59], v[136:139], v[160:163], v[56:59]
	v_mfma_f32_16x16x32_bf16 v[44:47], v[128:131], v[168:171], v[44:47]
	v_mfma_f32_16x16x32_bf16 v[40:43], v[136:139], v[168:171], v[40:43]
	v_mfma_f32_16x16x32_bf16 v[28:31], v[128:131], v[176:179], v[28:31]
	v_mfma_f32_16x16x32_bf16 v[24:27], v[136:139], v[176:179], v[24:27]
	v_mfma_f32_16x16x32_bf16 v[12:15], v[128:131], v[184:187], v[12:15]
	v_mfma_f32_16x16x32_bf16 v[8:11], v[136:139], v[184:187], v[8:11]
	v_mfma_f32_16x16x32_bf16 v[60:63], v[132:135], v[164:167], v[60:63]
	v_mfma_f32_16x16x32_bf16 v[56:59], v[140:143], v[164:167], v[56:59]
	v_mfma_f32_16x16x32_bf16 v[44:47], v[132:135], v[172:175], v[44:47]
	v_mfma_f32_16x16x32_bf16 v[40:43], v[140:143], v[172:175], v[40:43]
	v_mfma_f32_16x16x32_bf16 v[28:31], v[132:135], v[180:183], v[28:31]
	v_mfma_f32_16x16x32_bf16 v[24:27], v[140:143], v[180:183], v[24:27]
	v_mfma_f32_16x16x32_bf16 v[12:15], v[132:135], v[188:191], v[12:15]
	v_mfma_f32_16x16x32_bf16 v[8:11], v[140:143], v[188:191], v[8:11]
	v_mfma_f32_16x16x32_bf16 v[52:55], v[144:147], v[160:163], v[52:55]
	v_mfma_f32_16x16x32_bf16 v[48:51], v[152:155], v[160:163], v[48:51]
	v_mfma_f32_16x16x32_bf16 v[36:39], v[144:147], v[168:171], v[36:39]
	v_mfma_f32_16x16x32_bf16 v[32:35], v[152:155], v[168:171], v[32:35]
	v_mfma_f32_16x16x32_bf16 v[20:23], v[144:147], v[176:179], v[20:23]
	v_mfma_f32_16x16x32_bf16 v[16:19], v[152:155], v[176:179], v[16:19]
	v_mfma_f32_16x16x32_bf16 v[4:7], v[144:147], v[184:187], v[4:7]
	v_mfma_f32_16x16x32_bf16 v[0:3], v[152:155], v[184:187], v[0:3]
	v_mfma_f32_16x16x32_bf16 v[52:55], v[148:151], v[164:167], v[52:55]
	v_mfma_f32_16x16x32_bf16 v[48:51], v[156:159], v[164:167], v[48:51]
	v_mfma_f32_16x16x32_bf16 v[36:39], v[148:151], v[172:175], v[36:39]
	v_mfma_f32_16x16x32_bf16 v[32:35], v[156:159], v[172:175], v[32:35]
	v_mfma_f32_16x16x32_bf16 v[20:23], v[148:151], v[180:183], v[20:23]
	v_mfma_f32_16x16x32_bf16 v[16:19], v[156:159], v[180:183], v[16:19]
	v_mfma_f32_16x16x32_bf16 v[4:7], v[148:151], v[188:191], v[4:7]
	v_mfma_f32_16x16x32_bf16 v[0:3], v[156:159], v[188:191], v[0:3]
	s_setprio 0
	s_barrier
	s_add_i32 s61, s61, 2
	s_add_u32 s8, s8, 0x100
	s_addc_u32 s9, s9, 0
	s_add_u32 s59, s59, 0x100
	s_addc_u32 s60, s60, 0
	s_cmp_gt_u32 s61, 13
	s_cbranch_scc0 .LBB0_606
	s_and_b64 vcc, exec, s[18:19]
	s_cbranch_vccz .LBB0_609
	s_barrier

.LBB0_740:
	ds_read_b128 v[44:47], v205
	ds_read_b128 v[48:51], v205 offset:1024
	ds_read_b128 v[52:55], v205 offset:2048
	ds_read_b128 v[56:59], v205 offset:3072
	ds_read_b128 v[60:63], v206
	ds_read_b128 v[64:67], v206 offset:1024
	ds_read_b128 v[68:71], v206 offset:2048
	ds_read_b128 v[160:163], v206 offset:3072
	s_add_u32 s12, s10, s8
	s_addc_u32 s13, s11, s9
	s_add_u32 s12, s12, 0x100
	s_addc_u32 s13, s13, 0
	s_add_u32 s63, s19, s8
	s_addc_u32 vcc_lo, s55, s9
	s_cmpk_eq_i32 s8, 0x700
	s_cselect_b32 s15, s59, s13
	s_cselect_b32 s14, s58, s12
	s_cselect_b32 s4, s57, s1
	s_cselect_b32 s5, s56, s0
	s_cselect_b32 s13, s3, vcc_lo
	s_cselect_b32 s12, s18, s63
	s_cselect_b32 s63, s97, s17
	v_lshl_add_u64 v[224:225], v[42:43], 0, s[8:9]
	s_add_i32 m0, s65, 0xc000
	ds_read_b128 v[164:167], v207
	ds_read_b128 v[168:171], v207 offset:1024
	ds_read_b128 v[172:175], v207 offset:2048
	ds_read_b128 v[194:197], v207 offset:3072
	ds_read_b128 v[198:201], v207 offset:4096
	ds_read_b128 v[210:213], v207 offset:5120
	ds_read_b128 v[214:217], v207 offset:6144
	ds_read_b128 v[218:221], v207 offset:7168
	global_load_lds_dwordx4 v[224:225], off
	v_lshl_add_u64 v[224:225], v[40:41], 0, s[8:9]
	s_add_i32 m0, s65, 0xe000
	s_nop 0
	global_load_lds_dwordx4 v[224:225], off
	s_waitcnt vmcnt(8)
	s_waitcnt lgkmcnt(0)
	s_barrier
	s_setprio 1
	s_waitcnt lgkmcnt(0)
	v_mfma_f32_16x16x32_bf16 v[156:159], v[44:47], v[164:167], v[156:159]
	v_mfma_f32_16x16x32_bf16 v[152:155], v[52:55], v[164:167], v[152:155]
	v_mfma_f32_16x16x32_bf16 v[140:143], v[44:47], v[172:175], v[140:143]
	v_mfma_f32_16x16x32_bf16 v[136:139], v[52:55], v[172:175], v[136:139]
	v_mfma_f32_16x16x32_bf16 v[124:127], v[44:47], v[198:201], v[124:127]
	v_mfma_f32_16x16x32_bf16 v[120:123], v[52:55], v[198:201], v[120:123]
	v_readlane_b32 s32, v247, 60
	s_add_i32 s32, s32, -1
	v_readlane_b32 s100, v247, 61
	s_min_u32 s32, s32, s100
	v_readlane_b32 s100, v247, 62
	s_add_i32 s32, s32, s100
	s_min_u32 s32, s32, 0x2f6f
	s_lshr_b32 s100, s32, 1
	s_add_i32 s100, s100, 0x2808
	s_mul_i32 s101, s100, 0x8081
	s_lshr_b32 s101, s101, 24
	s_mul_i32 s98, s101, 0x1fe
	s_sub_i32 s100, s100, s98
	s_lshl_b32 s101, s101, 22
	s_lshl_b32 s100, s100, 13
	s_add_u32 s100, s100, s101
	s_bitcmp1_b32 s32, 0
	s_cselect_b32 s98, s66, s70
	s_cselect_b32 s99, s67, s71
	s_add_u32 s98, s98, s100
	s_addc_u32 s99, s99, 0
	v_lshlrev_b32_e32 v236, 4, v222
	global_store_dwordx4 v236, v[252:255], s[98:99] nt
	v_readlane_b32 s32, v247, 60
	v_readlane_b32 s100, v247, 61
	s_min_u32 s32, s32, s100
	v_readlane_b32 s100, v247, 62
	s_add_i32 s32, s32, s100
	s_min_u32 s32, s32, 0x2f6f
	s_lshr_b32 s100, s32, 1
	s_add_i32 s100, s100, 0x2808
	s_mul_i32 s101, s100, 0x8081
	s_lshr_b32 s101, s101, 24
	s_mul_i32 s98, s101, 0x1fe
	s_sub_i32 s100, s100, s98
	s_lshl_b32 s101, s101, 22
	s_lshl_b32 s100, s100, 13
	s_add_u32 s100, s100, s101
	s_bitcmp1_b32 s32, 0
	s_cselect_b32 s98, s84, s82
	s_cselect_b32 s99, s85, s83
	s_add_u32 s98, s98, s100
	s_addc_u32 s99, s99, 0
	s_add_u32 s98, s98, 0x4000
	s_addc_u32 s99, s99, 0
	v_lshlrev_b32_e32 v236, 4, v222
	global_load_dwordx4 v[252:255], v236, s[98:99] nt
	v_readlane_b32 s32, v247, 60
	s_add_i32 s32, s32, 1
	v_writelane_b32 v247, s32, 60
	s_nop 0
	v_mfma_f32_16x16x32_bf16 v[108:111], v[44:47], v[214:217], v[108:111]
	v_mfma_f32_16x16x32_bf16 v[104:107], v[52:55], v[214:217], v[104:107]
	v_mfma_f32_16x16x32_bf16 v[156:159], v[48:51], v[168:171], v[156:159]
	v_mfma_f32_16x16x32_bf16 v[152:155], v[56:59], v[168:171], v[152:155]
	v_mfma_f32_16x16x32_bf16 v[140:143], v[48:51], v[194:197], v[140:143]
	v_mfma_f32_16x16x32_bf16 v[136:139], v[56:59], v[194:197], v[136:139]
	v_mfma_f32_16x16x32_bf16 v[124:127], v[48:51], v[210:213], v[124:127]
	v_mfma_f32_16x16x32_bf16 v[120:123], v[56:59], v[210:213], v[120:123]
	v_mfma_f32_16x16x32_bf16 v[108:111], v[48:51], v[218:221], v[108:111]
	v_mfma_f32_16x16x32_bf16 v[104:107], v[56:59], v[218:221], v[104:107]
	v_mfma_f32_16x16x32_bf16 v[148:151], v[60:63], v[164:167], v[148:151]
	v_mfma_f32_16x16x32_bf16 v[144:147], v[68:71], v[164:167], v[144:147]
	v_mfma_f32_16x16x32_bf16 v[132:135], v[60:63], v[172:175], v[132:135]
	v_mfma_f32_16x16x32_bf16 v[128:131], v[68:71], v[172:175], v[128:131]
	v_mfma_f32_16x16x32_bf16 v[116:119], v[60:63], v[198:201], v[116:119]
	v_mfma_f32_16x16x32_bf16 v[112:115], v[68:71], v[198:201], v[112:115]
	v_mfma_f32_16x16x32_bf16 v[100:103], v[60:63], v[214:217], v[100:103]
	v_mfma_f32_16x16x32_bf16 v[96:99], v[68:71], v[214:217], v[96:99]
	v_mfma_f32_16x16x32_bf16 v[148:151], v[64:67], v[168:171], v[148:151]
	v_mfma_f32_16x16x32_bf16 v[144:147], v[160:163], v[168:171], v[144:147]
	v_mfma_f32_16x16x32_bf16 v[132:135], v[64:67], v[194:197], v[132:135]
	v_mfma_f32_16x16x32_bf16 v[128:131], v[160:163], v[194:197], v[128:131]
	v_mfma_f32_16x16x32_bf16 v[116:119], v[64:67], v[210:213], v[116:119]
	v_mfma_f32_16x16x32_bf16 v[112:115], v[160:163], v[210:213], v[112:115]
	v_mfma_f32_16x16x32_bf16 v[100:103], v[64:67], v[218:221], v[100:103]
	v_mfma_f32_16x16x32_bf16 v[96:99], v[160:163], v[218:221], v[96:99]
	s_setprio 0
	s_barrier
	s_add_i32 vcc_lo, s88, s33
	v_lshl_add_u64 v[228:229], s[12:13], 0, v[178:179]
	s_mov_b32 m0, vcc_lo
	ds_read_b128 v[164:167], v207 offset:16384
	ds_read_b128 v[168:171], v207 offset:17408
	ds_read_b128 v[172:175], v207 offset:18432
	ds_read_b128 v[194:197], v207 offset:19456
	ds_read_b128 v[198:201], v207 offset:20480
	ds_read_b128 v[210:213], v207 offset:21504
	ds_read_b128 v[214:217], v207 offset:22528
	ds_read_b128 v[218:221], v207 offset:23552
	global_load_lds_dwordx4 v[228:229], off
	s_add_i32 m0, vcc_lo, 0x2000
	s_add_u32 vcc_lo, s12, 0x40000
	v_lshl_add_u64 v[230:231], s[12:13], 0, v[182:183]
	s_addc_u32 vcc_hi, s13, 0
	s_add_i32 s36, s89, s33
	global_load_lds_dwordx4 v[230:231], off
	v_lshl_add_u64 v[224:225], vcc, 0, v[178:179]
	s_mov_b32 m0, s36
	v_lshl_add_u64 v[232:233], s[14:15], 0, v[176:177]
	global_load_lds_dwordx4 v[224:225], off
	s_add_i32 m0, s36, 0x2000
	v_lshl_add_u64 v[224:225], vcc, 0, v[182:183]
	s_sub_u32 vcc_lo, 0, s63
	global_load_lds_dwordx4 v[224:225], off
	s_mov_b32 m0, s65
	v_lshl_add_u64 v[224:225], s[14:15], 0, v[180:181]
	s_subb_u32 vcc_hi, 0, 0
	global_load_lds_dwordx4 v[232:233], off
	v_lshl_add_u64 v[234:235], v[224:225], 0, vcc
	s_mov_b32 m0, s68
	s_nop 0
	global_load_lds_dwordx4 v[234:235], off
	s_waitcnt vmcnt(10)
	s_waitcnt lgkmcnt(0)
	s_barrier
	s_setprio 1
	s_waitcnt lgkmcnt(0)
	v_mfma_f32_16x16x32_bf16 v[92:95], v[44:47], v[164:167], v[92:95]
	v_mfma_f32_16x16x32_bf16 v[88:91], v[52:55], v[164:167], v[88:91]
	v_mfma_f32_16x16x32_bf16 v[76:79], v[44:47], v[172:175], v[76:79]
	v_mfma_f32_16x16x32_bf16 v[72:75], v[52:55], v[172:175], v[72:75]
	v_mfma_f32_16x16x32_bf16 v[28:31], v[44:47], v[198:201], v[28:31]
	v_mfma_f32_16x16x32_bf16 v[24:27], v[52:55], v[198:201], v[24:27]
	v_mfma_f32_16x16x32_bf16 v[12:15], v[44:47], v[214:217], v[12:15]
	v_mfma_f32_16x16x32_bf16 v[8:11], v[52:55], v[214:217], v[8:11]
	v_mfma_f32_16x16x32_bf16 v[92:95], v[48:51], v[168:171], v[92:95]
	v_mfma_f32_16x16x32_bf16 v[88:91], v[56:59], v[168:171], v[88:91]
	v_mfma_f32_16x16x32_bf16 v[76:79], v[48:51], v[194:197], v[76:79]
	v_mfma_f32_16x16x32_bf16 v[72:75], v[56:59], v[194:197], v[72:75]
	v_mfma_f32_16x16x32_bf16 v[28:31], v[48:51], v[210:213], v[28:31]
	v_mfma_f32_16x16x32_bf16 v[24:27], v[56:59], v[210:213], v[24:27]
	v_mfma_f32_16x16x32_bf16 v[12:15], v[48:51], v[218:221], v[12:15]
	v_mfma_f32_16x16x32_bf16 v[8:11], v[56:59], v[218:221], v[8:11]
	v_mfma_f32_16x16x32_bf16 v[36:39], v[60:63], v[172:175], v[36:39]
	v_mfma_f32_16x16x32_bf16 v[32:35], v[68:71], v[172:175], v[32:35]
	v_mfma_f32_16x16x32_bf16 v[20:23], v[60:63], v[198:201], v[20:23]
	v_mfma_f32_16x16x32_bf16 v[16:19], v[68:71], v[198:201], v[16:19]
	v_mfma_f32_16x16x32_bf16 v[4:7], v[60:63], v[214:217], v[4:7]
	v_mfma_f32_16x16x32_bf16 v[0:3], v[68:71], v[214:217], v[0:3]
	v_mfma_f32_16x16x32_bf16 v[44:47], v[60:63], v[164:167], v[84:87]
	v_mfma_f32_16x16x32_bf16 v[48:51], v[68:71], v[164:167], v[80:83]
	v_mfma_f32_16x16x32_bf16 v[36:39], v[64:67], v[194:197], v[36:39]
	v_mfma_f32_16x16x32_bf16 v[32:35], v[160:163], v[194:197], v[32:35]
	v_mfma_f32_16x16x32_bf16 v[20:23], v[64:67], v[210:213], v[20:23]
	v_mfma_f32_16x16x32_bf16 v[16:19], v[160:163], v[210:213], v[16:19]
	v_mfma_f32_16x16x32_bf16 v[4:7], v[64:67], v[218:221], v[4:7]
	v_mfma_f32_16x16x32_bf16 v[0:3], v[160:163], v[218:221], v[0:3]
	v_mfma_f32_16x16x32_bf16 v[44:47], v[64:67], v[168:171], v[44:47]
	v_mfma_f32_16x16x32_bf16 v[48:51], v[160:163], v[168:171], v[48:51]
	s_setprio 0
	s_barrier
	s_add_i32 s36, 0, 0x18000
	s_add_i32 s37, 0, 0x1c000
	v_add_u32_e32 v64, s36, v204
	v_add_u32_e32 v80, s37, v204
	ds_read_b128 v[52:55], v64
	ds_read_b128 v[56:59], v64 offset:1024
	ds_read_b128 v[60:63], v64 offset:2048
	ds_read_b128 v[64:67], v64 offset:3072
	ds_read_b128 v[68:71], v80
	ds_read_b128 v[160:163], v80 offset:1024
	ds_read_b128 v[164:167], v80 offset:2048
	ds_read_b128 v[168:171], v80 offset:3072
	s_add_u32 s14, s14, s5
	s_addc_u32 s15, s15, s4
	s_mov_b32 m0, s69
	v_lshl_add_u64 v[224:225], s[14:15], 0, v[176:177]
	ds_read_b128 v[80:83], v207 offset:32768
	ds_read_b128 v[84:87], v207 offset:33792
	ds_read_b128 v[172:175], v207 offset:34816
	ds_read_b128 v[194:197], v207 offset:35840
	ds_read_b128 v[198:201], v207 offset:36864
	ds_read_b128 v[210:213], v207 offset:37888
	ds_read_b128 v[214:217], v207 offset:38912
	ds_read_b128 v[218:221], v207 offset:39936
	global_load_lds_dwordx4 v[224:225], off
	v_lshl_add_u64 v[224:225], s[14:15], 0, v[180:181]
	v_lshl_add_u64 v[224:225], v[224:225], 0, vcc
	s_mov_b32 m0, s72
	s_nop 0
	global_load_lds_dwordx4 v[224:225], off
	s_waitcnt vmcnt(10)
	s_waitcnt lgkmcnt(0)
	s_barrier
	s_setprio 1
	s_waitcnt lgkmcnt(0)
	v_mfma_f32_16x16x32_bf16 v[156:159], v[52:55], v[80:83], v[156:159]
	v_mfma_f32_16x16x32_bf16 v[152:155], v[60:63], v[80:83], v[152:155]
	v_mfma_f32_16x16x32_bf16 v[140:143], v[52:55], v[172:175], v[140:143]
	v_mfma_f32_16x16x32_bf16 v[136:139], v[60:63], v[172:175], v[136:139]
	v_mfma_f32_16x16x32_bf16 v[124:127], v[52:55], v[198:201], v[124:127]
	v_mfma_f32_16x16x32_bf16 v[120:123], v[60:63], v[198:201], v[120:123]
	v_mfma_f32_16x16x32_bf16 v[108:111], v[52:55], v[214:217], v[108:111]
	v_mfma_f32_16x16x32_bf16 v[104:107], v[60:63], v[214:217], v[104:107]
	v_mfma_f32_16x16x32_bf16 v[156:159], v[56:59], v[84:87], v[156:159]
	v_mfma_f32_16x16x32_bf16 v[152:155], v[64:67], v[84:87], v[152:155]
	v_mfma_f32_16x16x32_bf16 v[140:143], v[56:59], v[194:197], v[140:143]
	v_mfma_f32_16x16x32_bf16 v[136:139], v[64:67], v[194:197], v[136:139]
	v_mfma_f32_16x16x32_bf16 v[124:127], v[56:59], v[210:213], v[124:127]
	v_mfma_f32_16x16x32_bf16 v[120:123], v[64:67], v[210:213], v[120:123]
	v_mfma_f32_16x16x32_bf16 v[108:111], v[56:59], v[218:221], v[108:111]
	v_mfma_f32_16x16x32_bf16 v[104:107], v[64:67], v[218:221], v[104:107]
	v_mfma_f32_16x16x32_bf16 v[148:151], v[68:71], v[80:83], v[148:151]
	v_mfma_f32_16x16x32_bf16 v[80:83], v[164:167], v[80:83], v[144:147]
	v_mfma_f32_16x16x32_bf16 v[144:147], v[168:171], v[84:87], v[80:83]
	v_mfma_f32_16x16x32_bf16 v[80:83], v[68:71], v[172:175], v[132:135]
	v_mfma_f32_16x16x32_bf16 v[132:135], v[160:163], v[194:197], v[80:83]
	v_mfma_f32_16x16x32_bf16 v[80:83], v[164:167], v[172:175], v[128:131]
	v_mfma_f32_16x16x32_bf16 v[128:131], v[168:171], v[194:197], v[80:83]
	v_mfma_f32_16x16x32_bf16 v[80:83], v[68:71], v[198:201], v[116:119]
	v_mfma_f32_16x16x32_bf16 v[116:119], v[160:163], v[210:213], v[80:83]
	v_mfma_f32_16x16x32_bf16 v[80:83], v[164:167], v[198:201], v[112:115]
	v_mfma_f32_16x16x32_bf16 v[112:115], v[168:171], v[210:213], v[80:83]
	v_mfma_f32_16x16x32_bf16 v[80:83], v[68:71], v[214:217], v[100:103]
	v_mfma_f32_16x16x32_bf16 v[100:103], v[160:163], v[218:221], v[80:83]
	v_mfma_f32_16x16x32_bf16 v[80:83], v[164:167], v[214:217], v[96:99]
	v_mfma_f32_16x16x32_bf16 v[148:151], v[160:163], v[84:87], v[148:151]
	v_mfma_f32_16x16x32_bf16 v[96:99], v[168:171], v[218:221], v[80:83]
	s_setprio 0
	s_barrier
	s_add_i32 s4, s36, s33
	v_lshl_add_u64 v[84:85], v[228:229], 0, s[50:51]
	s_mov_b32 m0, s4
	s_nop 0
	ds_read_b128 v[80:83], v207 offset:49152
	ds_read_b128 v[172:175], v207 offset:50176
	ds_read_b128 v[194:197], v207 offset:51200
	ds_read_b128 v[198:201], v207 offset:52224
	ds_read_b128 v[210:213], v207 offset:53248
	ds_read_b128 v[214:217], v207 offset:54272
	ds_read_b128 v[218:221], v207 offset:55296
	ds_read_b128 v[224:227], v207 offset:56320
	global_load_lds_dwordx4 v[84:85], off
	s_add_i32 m0, s4, 0x2000
	s_add_u32 s12, s12, 0x40080
	v_lshl_add_u64 v[84:85], v[230:231], 0, s[50:51]
	s_addc_u32 s13, s13, 0
	s_add_i32 s4, s37, s33
	global_load_lds_dwordx4 v[84:85], off
	v_lshl_add_u64 v[84:85], s[12:13], 0, v[178:179]
	s_mov_b32 m0, s4
	s_nop 0
	global_load_lds_dwordx4 v[84:85], off
	v_lshl_add_u64 v[84:85], s[12:13], 0, v[182:183]
	s_add_i32 m0, s4, 0x2000
	s_nop 0
	global_load_lds_dwordx4 v[84:85], off
	v_lshl_add_u64 v[84:85], v[232:233], 0, s[50:51]
	s_mov_b32 m0, s75
	s_nop 0
	global_load_lds_dwordx4 v[84:85], off
	v_lshl_add_u64 v[84:85], v[234:235], 0, s[50:51]
	s_mov_b32 m0, s76
	s_nop 0
	global_load_lds_dwordx4 v[84:85], off
	s_waitcnt vmcnt(8)
	s_waitcnt lgkmcnt(0)
	s_barrier
	s_setprio 1
	s_waitcnt lgkmcnt(0)
	v_mfma_f32_16x16x32_bf16 v[84:87], v[52:55], v[80:83], v[92:95]
	v_mfma_f32_16x16x32_bf16 v[92:95], v[56:59], v[172:175], v[84:87]
	v_mfma_f32_16x16x32_bf16 v[84:87], v[60:63], v[80:83], v[88:91]
	v_mfma_f32_16x16x32_bf16 v[76:79], v[52:55], v[194:197], v[76:79]
	v_mfma_f32_16x16x32_bf16 v[72:75], v[60:63], v[194:197], v[72:75]
	v_mfma_f32_16x16x32_bf16 v[28:31], v[52:55], v[210:213], v[28:31]
	v_mfma_f32_16x16x32_bf16 v[24:27], v[60:63], v[210:213], v[24:27]
	v_mfma_f32_16x16x32_bf16 v[12:15], v[52:55], v[218:221], v[12:15]
	v_mfma_f32_16x16x32_bf16 v[8:11], v[60:63], v[218:221], v[8:11]
	v_mfma_f32_16x16x32_bf16 v[88:91], v[64:67], v[172:175], v[84:87]
	v_mfma_f32_16x16x32_bf16 v[76:79], v[56:59], v[198:201], v[76:79]
	v_mfma_f32_16x16x32_bf16 v[72:75], v[64:67], v[198:201], v[72:75]
	v_mfma_f32_16x16x32_bf16 v[28:31], v[56:59], v[214:217], v[28:31]
	v_mfma_f32_16x16x32_bf16 v[24:27], v[64:67], v[214:217], v[24:27]
	v_mfma_f32_16x16x32_bf16 v[12:15], v[56:59], v[224:227], v[12:15]
	v_mfma_f32_16x16x32_bf16 v[8:11], v[64:67], v[224:227], v[8:11]
	v_mfma_f32_16x16x32_bf16 v[44:47], v[68:71], v[80:83], v[44:47]
	v_mfma_f32_16x16x32_bf16 v[84:87], v[160:163], v[172:175], v[44:47]
	v_mfma_f32_16x16x32_bf16 v[44:47], v[164:167], v[80:83], v[48:51]
	v_mfma_f32_16x16x32_bf16 v[36:39], v[68:71], v[194:197], v[36:39]
	v_mfma_f32_16x16x32_bf16 v[32:35], v[164:167], v[194:197], v[32:35]
	v_mfma_f32_16x16x32_bf16 v[20:23], v[68:71], v[210:213], v[20:23]
	v_mfma_f32_16x16x32_bf16 v[16:19], v[164:167], v[210:213], v[16:19]
	v_mfma_f32_16x16x32_bf16 v[4:7], v[68:71], v[218:221], v[4:7]
	v_mfma_f32_16x16x32_bf16 v[0:3], v[164:167], v[218:221], v[0:3]
	v_mfma_f32_16x16x32_bf16 v[80:83], v[168:171], v[172:175], v[44:47]
	v_mfma_f32_16x16x32_bf16 v[36:39], v[160:163], v[198:201], v[36:39]
	v_mfma_f32_16x16x32_bf16 v[32:35], v[168:171], v[198:201], v[32:35]
	v_mfma_f32_16x16x32_bf16 v[20:23], v[160:163], v[214:217], v[20:23]
	v_mfma_f32_16x16x32_bf16 v[16:19], v[168:171], v[214:217], v[16:19]
	v_mfma_f32_16x16x32_bf16 v[4:7], v[160:163], v[224:227], v[4:7]
	v_mfma_f32_16x16x32_bf16 v[0:3], v[168:171], v[224:227], v[0:3]
	s_setprio 0
	s_barrier
	s_add_i32 s62, s62, 2
	s_add_u32 s8, s8, 0x100
	s_addc_u32 s9, s9, 0
	s_cmp_gt_u32 s62, 13
	s_cbranch_scc0 .LBB0_740
	s_and_b64 vcc, exec, s[52:53]
	s_cbranch_vccz .LBB0_743
	s_barrier

.LBB0_1044:
	ds_read_b128 v[128:131], v230
	ds_read_b128 v[132:135], v230 offset:1024
	ds_read_b128 v[136:139], v230 offset:2048
	ds_read_b128 v[140:143], v230 offset:3072
	ds_read_b128 v[144:147], v231
	ds_read_b128 v[148:151], v231 offset:1024
	ds_read_b128 v[152:155], v231 offset:2048
	ds_read_b128 v[156:159], v231 offset:3072
	s_add_u32 s24, s2, 0x100
	s_addc_u32 s25, s3, 0
	s_cmp_eq_u32 s61, s101
	s_cselect_b32 s35, s7, s25
	s_cselect_b32 s34, s6, s24
	s_cselect_b32 s27, s19, s60
	s_cselect_b32 s26, s18, s59
	v_lshl_add_u64 v[208:209], s[2:3], 0, v[200:201]
	s_add_i32 m0, s36, 0xc000
	ds_read_b128 v[160:163], v232
	ds_read_b128 v[164:167], v232 offset:1024
	ds_read_b128 v[168:171], v232 offset:2048
	ds_read_b128 v[172:175], v232 offset:3072
	ds_read_b128 v[176:179], v232 offset:4096
	ds_read_b128 v[180:183], v232 offset:5120
	ds_read_b128 v[184:187], v232 offset:6144
	ds_read_b128 v[188:191], v232 offset:7168
	global_load_lds_dwordx4 v[208:209], off
	v_lshl_add_u64 v[208:209], s[2:3], 0, v[202:203]
	s_add_i32 m0, s36, 0xe000
	s_nop 0
	global_load_lds_dwordx4 v[208:209], off
	s_waitcnt vmcnt(8)
	s_waitcnt lgkmcnt(0)
	s_barrier
	s_setprio 1
	s_waitcnt lgkmcnt(0)
	v_mfma_f32_16x16x32_bf16 v[124:127], v[128:131], v[160:163], v[124:127]
	v_mfma_f32_16x16x32_bf16 v[120:123], v[136:139], v[160:163], v[120:123]
	v_mfma_f32_16x16x32_bf16 v[108:111], v[128:131], v[168:171], v[108:111]
	v_mfma_f32_16x16x32_bf16 v[104:107], v[136:139], v[168:171], v[104:107]
	v_mfma_f32_16x16x32_bf16 v[92:95], v[128:131], v[176:179], v[92:95]
	v_mfma_f32_16x16x32_bf16 v[88:91], v[136:139], v[176:179], v[88:91]
	v_mfma_f32_16x16x32_bf16 v[76:79], v[128:131], v[184:187], v[76:79]
	v_mfma_f32_16x16x32_bf16 v[72:75], v[136:139], v[184:187], v[72:75]
	v_mfma_f32_16x16x32_bf16 v[124:127], v[132:135], v[164:167], v[124:127]
	v_mfma_f32_16x16x32_bf16 v[120:123], v[140:143], v[164:167], v[120:123]
	v_mfma_f32_16x16x32_bf16 v[108:111], v[132:135], v[172:175], v[108:111]
	v_mfma_f32_16x16x32_bf16 v[104:107], v[140:143], v[172:175], v[104:107]
	v_mfma_f32_16x16x32_bf16 v[92:95], v[132:135], v[180:183], v[92:95]
	v_mfma_f32_16x16x32_bf16 v[88:91], v[140:143], v[180:183], v[88:91]
	v_mfma_f32_16x16x32_bf16 v[76:79], v[132:135], v[188:191], v[76:79]
	v_mfma_f32_16x16x32_bf16 v[72:75], v[140:143], v[188:191], v[72:75]
	v_mfma_f32_16x16x32_bf16 v[116:119], v[144:147], v[160:163], v[116:119]
	v_mfma_f32_16x16x32_bf16 v[112:115], v[152:155], v[160:163], v[112:115]
	v_mfma_f32_16x16x32_bf16 v[100:103], v[144:147], v[168:171], v[100:103]
	v_mfma_f32_16x16x32_bf16 v[96:99], v[152:155], v[168:171], v[96:99]
	v_mfma_f32_16x16x32_bf16 v[84:87], v[144:147], v[176:179], v[84:87]
	v_mfma_f32_16x16x32_bf16 v[80:83], v[152:155], v[176:179], v[80:83]
	v_mfma_f32_16x16x32_bf16 v[68:71], v[144:147], v[184:187], v[68:71]
	v_mfma_f32_16x16x32_bf16 v[64:67], v[152:155], v[184:187], v[64:67]
	v_mfma_f32_16x16x32_bf16 v[116:119], v[148:151], v[164:167], v[116:119]
	v_mfma_f32_16x16x32_bf16 v[112:115], v[156:159], v[164:167], v[112:115]
	v_mfma_f32_16x16x32_bf16 v[100:103], v[148:151], v[172:175], v[100:103]
	v_mfma_f32_16x16x32_bf16 v[96:99], v[156:159], v[172:175], v[96:99]
	v_mfma_f32_16x16x32_bf16 v[84:87], v[148:151], v[180:183], v[84:87]
	v_mfma_f32_16x16x32_bf16 v[80:83], v[156:159], v[180:183], v[80:83]
	v_mfma_f32_16x16x32_bf16 v[68:71], v[148:151], v[188:191], v[68:71]
	v_mfma_f32_16x16x32_bf16 v[64:67], v[156:159], v[188:191], v[64:67]
	s_setprio 0
	s_barrier
	s_add_i32 s2, s49, s33
	v_lshl_add_u64 v[208:209], s[26:27], 0, v[194:195]
	s_mov_b32 m0, s2
	ds_read_b128 v[160:163], v232 offset:16384
	ds_read_b128 v[164:167], v232 offset:17408
	ds_read_b128 v[168:171], v232 offset:18432
	ds_read_b128 v[172:175], v232 offset:19456
	ds_read_b128 v[176:179], v232 offset:20480
	ds_read_b128 v[180:183], v232 offset:21504
	ds_read_b128 v[184:187], v232 offset:22528
	ds_read_b128 v[188:191], v232 offset:23552
	global_load_lds_dwordx4 v[208:209], off
	s_add_i32 m0, s2, 0x2000
	s_add_u32 s2, s26, 0xb0000
	v_lshl_add_u64 v[210:211], s[26:27], 0, v[198:199]
	s_addc_u32 s3, s27, 0
	s_add_i32 s62, s50, s33
	global_load_lds_dwordx4 v[210:211], off
	v_lshl_add_u64 v[212:213], s[2:3], 0, v[194:195]
	s_mov_b32 m0, s62
	v_lshl_add_u64 v[214:215], s[34:35], 0, v[196:197]
	global_load_lds_dwordx4 v[212:213], off
	v_lshl_add_u64 v[212:213], s[2:3], 0, v[198:199]
	s_add_i32 m0, s62, 0x2000
	s_nop 0
	global_load_lds_dwordx4 v[212:213], off
	v_lshl_add_u64 v[212:213], s[34:35], 0, v[192:193]
	s_mov_b32 m0, s36
	s_nop 0
	global_load_lds_dwordx4 v[212:213], off
	s_mov_b32 m0, s37
	s_nop 0
	global_load_lds_dwordx4 v[214:215], off
	s_waitcnt vmcnt(8)
	s_waitcnt lgkmcnt(0)
	s_barrier
	s_setprio 1
	s_waitcnt lgkmcnt(0)
	v_mfma_f32_16x16x32_bf16 v[60:63], v[128:131], v[160:163], v[60:63]
	v_mfma_f32_16x16x32_bf16 v[56:59], v[136:139], v[160:163], v[56:59]
	v_mfma_f32_16x16x32_bf16 v[44:47], v[128:131], v[168:171], v[44:47]
	v_mfma_f32_16x16x32_bf16 v[40:43], v[136:139], v[168:171], v[40:43]
	v_mfma_f32_16x16x32_bf16 v[28:31], v[128:131], v[176:179], v[28:31]
	v_mfma_f32_16x16x32_bf16 v[24:27], v[136:139], v[176:179], v[24:27]
	v_mfma_f32_16x16x32_bf16 v[12:15], v[128:131], v[184:187], v[12:15]
	v_mfma_f32_16x16x32_bf16 v[8:11], v[136:139], v[184:187], v[8:11]
	v_mfma_f32_16x16x32_bf16 v[60:63], v[132:135], v[164:167], v[60:63]
	v_mfma_f32_16x16x32_bf16 v[56:59], v[140:143], v[164:167], v[56:59]
	v_mfma_f32_16x16x32_bf16 v[44:47], v[132:135], v[172:175], v[44:47]
	v_mfma_f32_16x16x32_bf16 v[40:43], v[140:143], v[172:175], v[40:43]
	v_mfma_f32_16x16x32_bf16 v[28:31], v[132:135], v[180:183], v[28:31]
	v_mfma_f32_16x16x32_bf16 v[24:27], v[140:143], v[180:183], v[24:27]
	v_mfma_f32_16x16x32_bf16 v[12:15], v[132:135], v[188:191], v[12:15]
	v_mfma_f32_16x16x32_bf16 v[8:11], v[140:143], v[188:191], v[8:11]
	v_mfma_f32_16x16x32_bf16 v[52:55], v[144:147], v[160:163], v[52:55]
	v_mfma_f32_16x16x32_bf16 v[48:51], v[152:155], v[160:163], v[48:51]
	v_mfma_f32_16x16x32_bf16 v[36:39], v[144:147], v[168:171], v[36:39]
	v_mfma_f32_16x16x32_bf16 v[32:35], v[152:155], v[168:171], v[32:35]
	v_mfma_f32_16x16x32_bf16 v[20:23], v[144:147], v[176:179], v[20:23]
	v_mfma_f32_16x16x32_bf16 v[16:19], v[152:155], v[176:179], v[16:19]
	v_mfma_f32_16x16x32_bf16 v[4:7], v[144:147], v[184:187], v[4:7]
	v_mfma_f32_16x16x32_bf16 v[0:3], v[152:155], v[184:187], v[0:3]
	v_mfma_f32_16x16x32_bf16 v[52:55], v[148:151], v[164:167], v[52:55]
	v_mfma_f32_16x16x32_bf16 v[48:51], v[156:159], v[164:167], v[48:51]
	v_mfma_f32_16x16x32_bf16 v[36:39], v[148:151], v[172:175], v[36:39]
	v_mfma_f32_16x16x32_bf16 v[32:35], v[156:159], v[172:175], v[32:35]
	v_mfma_f32_16x16x32_bf16 v[20:23], v[148:151], v[180:183], v[20:23]
	v_mfma_f32_16x16x32_bf16 v[16:19], v[156:159], v[180:183], v[16:19]
	v_mfma_f32_16x16x32_bf16 v[4:7], v[148:151], v[188:191], v[4:7]
	v_mfma_f32_16x16x32_bf16 v[0:3], v[156:159], v[188:191], v[0:3]
	s_setprio 0
	s_barrier
	s_add_i32 s62, 0, 0x18000
	s_add_i32 s63, 0, 0x1c000
	v_add_u32_e32 v140, s62, v228
	v_add_u32_e32 v156, s63, v228
	ds_read_b128 v[128:131], v140
	ds_read_b128 v[132:135], v140 offset:1024
	ds_read_b128 v[136:139], v140 offset:2048
	ds_read_b128 v[140:143], v140 offset:3072
	ds_read_b128 v[144:147], v156
	ds_read_b128 v[148:151], v156 offset:1024
	ds_read_b128 v[152:155], v156 offset:2048
	ds_read_b128 v[156:159], v156 offset:3072
	s_add_u32 s2, s34, 0xb0000
	s_addc_u32 s3, s35, 0
	s_mov_b32 m0, s38
	v_lshl_add_u64 v[216:217], s[2:3], 0, v[192:193]
	ds_read_b128 v[160:163], v232 offset:32768
	ds_read_b128 v[164:167], v232 offset:33792
	ds_read_b128 v[168:171], v232 offset:34816
	ds_read_b128 v[172:175], v232 offset:35840
	ds_read_b128 v[176:179], v232 offset:36864
	ds_read_b128 v[180:183], v232 offset:37888
	ds_read_b128 v[184:187], v232 offset:38912
	ds_read_b128 v[188:191], v232 offset:39936
	global_load_lds_dwordx4 v[216:217], off
	v_lshl_add_u64 v[216:217], s[2:3], 0, v[196:197]
	s_mov_b32 m0, s39
	s_nop 0
	global_load_lds_dwordx4 v[216:217], off
	s_waitcnt vmcnt(8)
	s_waitcnt lgkmcnt(0)
	s_barrier
	s_setprio 1
	s_waitcnt lgkmcnt(0)
	v_mfma_f32_16x16x32_bf16 v[124:127], v[128:131], v[160:163], v[124:127]
	v_mfma_f32_16x16x32_bf16 v[120:123], v[136:139], v[160:163], v[120:123]
	v_mfma_f32_16x16x32_bf16 v[108:111], v[128:131], v[168:171], v[108:111]
	v_mfma_f32_16x16x32_bf16 v[104:107], v[136:139], v[168:171], v[104:107]
	v_mfma_f32_16x16x32_bf16 v[92:95], v[128:131], v[176:179], v[92:95]
	v_mfma_f32_16x16x32_bf16 v[88:91], v[136:139], v[176:179], v[88:91]
	v_mfma_f32_16x16x32_bf16 v[76:79], v[128:131], v[184:187], v[76:79]
	v_mfma_f32_16x16x32_bf16 v[72:75], v[136:139], v[184:187], v[72:75]
	v_mfma_f32_16x16x32_bf16 v[124:127], v[132:135], v[164:167], v[124:127]
	v_mfma_f32_16x16x32_bf16 v[120:123], v[140:143], v[164:167], v[120:123]
	v_mfma_f32_16x16x32_bf16 v[108:111], v[132:135], v[172:175], v[108:111]
	v_mfma_f32_16x16x32_bf16 v[104:107], v[140:143], v[172:175], v[104:107]
	v_mfma_f32_16x16x32_bf16 v[92:95], v[132:135], v[180:183], v[92:95]
	v_mfma_f32_16x16x32_bf16 v[88:91], v[140:143], v[180:183], v[88:91]
	v_mfma_f32_16x16x32_bf16 v[76:79], v[132:135], v[188:191], v[76:79]
	v_mfma_f32_16x16x32_bf16 v[72:75], v[140:143], v[188:191], v[72:75]
	v_mfma_f32_16x16x32_bf16 v[116:119], v[144:147], v[160:163], v[116:119]
	v_mfma_f32_16x16x32_bf16 v[112:115], v[152:155], v[160:163], v[112:115]
	v_mfma_f32_16x16x32_bf16 v[100:103], v[144:147], v[168:171], v[100:103]
	v_mfma_f32_16x16x32_bf16 v[96:99], v[152:155], v[168:171], v[96:99]
	v_mfma_f32_16x16x32_bf16 v[84:87], v[144:147], v[176:179], v[84:87]
	v_mfma_f32_16x16x32_bf16 v[80:83], v[152:155], v[176:179], v[80:83]
	v_mfma_f32_16x16x32_bf16 v[68:71], v[144:147], v[184:187], v[68:71]
	v_mfma_f32_16x16x32_bf16 v[64:67], v[152:155], v[184:187], v[64:67]
	v_mfma_f32_16x16x32_bf16 v[116:119], v[148:151], v[164:167], v[116:119]
	v_mfma_f32_16x16x32_bf16 v[112:115], v[156:159], v[164:167], v[112:115]
	v_mfma_f32_16x16x32_bf16 v[100:103], v[148:151], v[172:175], v[100:103]
	v_mfma_f32_16x16x32_bf16 v[96:99], v[156:159], v[172:175], v[96:99]
	v_mfma_f32_16x16x32_bf16 v[84:87], v[148:151], v[180:183], v[84:87]
	v_mfma_f32_16x16x32_bf16 v[80:83], v[156:159], v[180:183], v[80:83]
	v_mfma_f32_16x16x32_bf16 v[68:71], v[148:151], v[188:191], v[68:71]
	v_mfma_f32_16x16x32_bf16 v[64:67], v[156:159], v[188:191], v[64:67]
	s_setprio 0
	s_barrier
	s_add_i32 s2, s62, s33
	v_lshl_add_u64 v[208:209], v[208:209], 0, s[12:13]
	s_mov_b32 m0, s2
	ds_read_b128 v[160:163], v232 offset:49152
	ds_read_b128 v[164:167], v232 offset:50176
	ds_read_b128 v[168:171], v232 offset:51200
	ds_read_b128 v[172:175], v232 offset:52224
	ds_read_b128 v[176:179], v232 offset:53248
	ds_read_b128 v[180:183], v232 offset:54272
	ds_read_b128 v[184:187], v232 offset:55296
	ds_read_b128 v[188:191], v232 offset:56320
	global_load_lds_dwordx4 v[208:209], off
	s_add_i32 m0, s2, 0x2000
	s_add_u32 s2, s26, 0xb0080
	v_lshl_add_u64 v[208:209], v[210:211], 0, s[12:13]
	s_addc_u32 s3, s27, 0
	s_add_i32 s26, s63, s33
	global_load_lds_dwordx4 v[208:209], off
	v_lshl_add_u64 v[208:209], s[2:3], 0, v[194:195]
	s_mov_b32 m0, s26
	s_nop 0
	global_load_lds_dwordx4 v[208:209], off
	v_lshl_add_u64 v[208:209], s[2:3], 0, v[198:199]
	s_add_i32 m0, s26, 0x2000
	s_nop 0
	global_load_lds_dwordx4 v[208:209], off
	v_lshl_add_u64 v[208:209], v[212:213], 0, s[12:13]
	s_mov_b32 m0, s46
	s_nop 0
	global_load_lds_dwordx4 v[208:209], off
	v_lshl_add_u64 v[208:209], v[214:215], 0, s[12:13]
	s_mov_b32 m0, s47
	s_nop 0
	global_load_lds_dwordx4 v[208:209], off
	s_waitcnt vmcnt(8)
	s_waitcnt lgkmcnt(0)
	s_barrier
	s_setprio 1
	s_waitcnt lgkmcnt(0)
	v_mfma_f32_16x16x32_bf16 v[60:63], v[128:131], v[160:163], v[60:63]
	v_mfma_f32_16x16x32_bf16 v[56:59], v[136:139], v[160:163], v[56:59]
	v_mfma_f32_16x16x32_bf16 v[44:47], v[128:131], v[168:171], v[44:47]
	v_mfma_f32_16x16x32_bf16 v[40:43], v[136:139], v[168:171], v[40:43]
	v_mfma_f32_16x16x32_bf16 v[28:31], v[128:131], v[176:179], v[28:31]
	v_mfma_f32_16x16x32_bf16 v[24:27], v[136:139], v[176:179], v[24:27]
	v_mfma_f32_16x16x32_bf16 v[12:15], v[128:131], v[184:187], v[12:15]
	v_mfma_f32_16x16x32_bf16 v[8:11], v[136:139], v[184:187], v[8:11]
	v_mfma_f32_16x16x32_bf16 v[60:63], v[132:135], v[164:167], v[60:63]
	v_mfma_f32_16x16x32_bf16 v[56:59], v[140:143], v[164:167], v[56:59]
	v_mfma_f32_16x16x32_bf16 v[44:47], v[132:135], v[172:175], v[44:47]
	v_mfma_f32_16x16x32_bf16 v[40:43], v[140:143], v[172:175], v[40:43]
	v_mfma_f32_16x16x32_bf16 v[28:31], v[132:135], v[180:183], v[28:31]
	v_mfma_f32_16x16x32_bf16 v[24:27], v[140:143], v[180:183], v[24:27]
	v_mfma_f32_16x16x32_bf16 v[12:15], v[132:135], v[188:191], v[12:15]
	v_mfma_f32_16x16x32_bf16 v[8:11], v[140:143], v[188:191], v[8:11]
	v_mfma_f32_16x16x32_bf16 v[52:55], v[144:147], v[160:163], v[52:55]
	v_mfma_f32_16x16x32_bf16 v[48:51], v[152:155], v[160:163], v[48:51]
	v_mfma_f32_16x16x32_bf16 v[36:39], v[144:147], v[168:171], v[36:39]
	v_mfma_f32_16x16x32_bf16 v[32:35], v[152:155], v[168:171], v[32:35]
	v_mfma_f32_16x16x32_bf16 v[20:23], v[144:147], v[176:179], v[20:23]
	v_mfma_f32_16x16x32_bf16 v[16:19], v[152:155], v[176:179], v[16:19]
	v_mfma_f32_16x16x32_bf16 v[4:7], v[144:147], v[184:187], v[4:7]
	v_mfma_f32_16x16x32_bf16 v[0:3], v[152:155], v[184:187], v[0:3]
	v_mfma_f32_16x16x32_bf16 v[52:55], v[148:151], v[164:167], v[52:55]
	v_mfma_f32_16x16x32_bf16 v[48:51], v[156:159], v[164:167], v[48:51]
	v_mfma_f32_16x16x32_bf16 v[36:39], v[148:151], v[172:175], v[36:39]
	v_mfma_f32_16x16x32_bf16 v[32:35], v[156:159], v[172:175], v[32:35]
	v_mfma_f32_16x16x32_bf16 v[20:23], v[148:151], v[180:183], v[20:23]
	v_mfma_f32_16x16x32_bf16 v[16:19], v[156:159], v[180:183], v[16:19]
	v_mfma_f32_16x16x32_bf16 v[4:7], v[148:151], v[188:191], v[4:7]
	v_mfma_f32_16x16x32_bf16 v[0:3], v[156:159], v[188:191], v[0:3]
	s_setprio 0
	s_barrier
	s_add_i32 s61, s61, 2
	s_add_u32 s59, s59, 0x100
	s_addc_u32 s60, s60, 0
	s_cmp_gt_u32 s61, s101
	s_mov_b64 s[2:3], s[24:25]
	s_cbranch_scc0 .LBB0_1044
	s_and_b64 vcc, exec, s[14:15]
	s_cbranch_vccz .LBB0_1047
	s_barrier
